# post0 rotary-table loads batched and mod0 partial-sum loads batched on top of v15 state-update pipelining
# speedup vs baseline: 1.0503x; 1.0034x over previous
.LBB0_144:
	s_or_b64 exec, exec, s[8:9]
	s_waitcnt vmcnt(1)
	v_lshlrev_b32_e32 v68, 16, v55
	v_and_b32_e32 v69, 0xffff0000, v55
	s_mov_b32 s8, 0x3d372713
	v_pk_mul_f32 v[70:71], v[68:69], s[8:9] op_sel_hi:[1,0]
	s_mov_b32 s12, 0x3f4c422a
	v_pk_mul_f32 v[70:71], v[70:71], v[68:69]
	s_mov_b32 s1, 0x800000
	v_pk_fma_f32 v[70:71], v[70:71], v[68:69], v[68:69]
	v_pk_mul_f32 v[68:69], v[68:69], 0.5 op_sel_hi:[1,0]
	v_pk_mul_f32 v[70:71], v[70:71], s[12:13] op_sel_hi:[1,0]
	s_nop 0
	v_mul_f32_e64 v55, |v70|, -2.0
	v_mul_f32_e32 v55, 0x3fb8aa3b, v55
	v_exp_f32_e32 v80, v55
	v_mul_f32_e64 v55, |v71|, -2.0
	v_mul_f32_e32 v55, 0x3fb8aa3b, v55
	v_exp_f32_e32 v81, v55
	v_add_f32_e32 v55, 1.0, v80
	v_rcp_f32_e32 v82, v55
	v_cmp_gt_f32_e32 vcc, 0, v71
	v_add_f32_e32 v55, 1.0, v81
	v_rcp_f32_e32 v83, v55
	v_pk_add_f32 v[80:81], v[80:81], 1.0 op_sel_hi:[1,0] neg_lo:[1,0] neg_hi:[1,0]
	s_nop 0
	v_pk_mul_f32 v[80:81], v[80:81], v[82:83]
	v_lshlrev_b32_e32 v82, 16, v54
	v_and_b32_e32 v83, 0xffff0000, v54
	v_pk_mul_f32 v[84:85], v[82:83], s[8:9] op_sel_hi:[1,0]
	v_cndmask_b32_e64 v55, v81, -v81, vcc
	v_pk_mul_f32 v[84:85], v[84:85], v[82:83]
	v_cmp_gt_f32_e32 vcc, 0, v70
	v_pk_fma_f32 v[84:85], v[84:85], v[82:83], v[82:83]
	v_pk_mul_f32 v[82:83], v[82:83], 0.5 op_sel_hi:[1,0]
	v_pk_mul_f32 v[84:85], v[84:85], s[12:13] op_sel_hi:[1,0]
	s_nop 0
	v_mul_f32_e64 v54, |v84|, -2.0
	v_mul_f32_e32 v54, 0x3fb8aa3b, v54
	v_exp_f32_e32 v86, v54
	v_mul_f32_e64 v54, |v85|, -2.0
	v_mul_f32_e32 v54, 0x3fb8aa3b, v54
	v_exp_f32_e32 v87, v54
	v_add_f32_e32 v70, 1.0, v86
	v_rcp_f32_e32 v70, v70
	v_cndmask_b32_e64 v54, v80, -v80, vcc
	v_add_f32_e32 v71, 1.0, v87
	v_rcp_f32_e32 v71, v71
	v_pk_add_f32 v[86:87], v[86:87], 1.0 op_sel_hi:[1,0] neg_lo:[1,0] neg_hi:[1,0]
	v_cmp_gt_f32_e32 vcc, 0, v85
	v_pk_add_f32 v[54:55], v[54:55], 1.0 op_sel_hi:[1,0]
	v_pk_mul_f32 v[70:71], v[86:87], v[70:71]
	v_lshlrev_b32_e32 v86, 16, v53
	v_and_b32_e32 v87, 0xffff0000, v53
	v_pk_mul_f32 v[88:89], v[86:87], s[8:9] op_sel_hi:[1,0]
	v_cndmask_b32_e64 v71, v71, -v71, vcc
	v_pk_mul_f32 v[88:89], v[88:89], v[86:87]
	v_cmp_gt_f32_e32 vcc, 0, v84
	v_pk_fma_f32 v[88:89], v[88:89], v[86:87], v[86:87]
	v_pk_mul_f32 v[86:87], v[86:87], 0.5 op_sel_hi:[1,0]
	v_pk_mul_f32 v[88:89], v[88:89], s[12:13] op_sel_hi:[1,0]
	v_cndmask_b32_e64 v70, v70, -v70, vcc
	v_mul_f32_e64 v53, |v88|, -2.0
	v_mul_f32_e32 v53, 0x3fb8aa3b, v53
	v_exp_f32_e32 v90, v53
	v_mul_f32_e64 v53, |v89|, -2.0
	v_mul_f32_e32 v53, 0x3fb8aa3b, v53
	v_exp_f32_e32 v91, v53
	v_add_f32_e32 v53, 1.0, v90
	v_rcp_f32_e32 v84, v53
	v_cmp_gt_f32_e32 vcc, 0, v89
	v_add_f32_e32 v53, 1.0, v91
	v_rcp_f32_e32 v85, v53
	v_pk_add_f32 v[90:91], v[90:91], 1.0 op_sel_hi:[1,0] neg_lo:[1,0] neg_hi:[1,0]
	v_pk_add_f32 v[70:71], v[70:71], 1.0 op_sel_hi:[1,0]
	v_pk_mul_f32 v[80:81], v[68:69], v[54:55]
	v_pk_mul_f32 v[84:85], v[90:91], v[84:85]
	v_lshlrev_b32_e32 v90, 16, v52
	v_and_b32_e32 v91, 0xffff0000, v52
	v_pk_mul_f32 v[94:95], v[90:91], s[8:9] op_sel_hi:[1,0]
	v_cndmask_b32_e64 v53, v85, -v85, vcc
	v_pk_mul_f32 v[94:95], v[94:95], v[90:91]
	v_cmp_gt_f32_e32 vcc, 0, v88
	v_pk_fma_f32 v[94:95], v[94:95], v[90:91], v[90:91]
	v_pk_mul_f32 v[90:91], v[90:91], 0.5 op_sel_hi:[1,0]
	v_pk_mul_f32 v[94:95], v[94:95], s[12:13] op_sel_hi:[1,0]
	v_pk_mul_f32 v[92:93], v[82:83], v[70:71]
	v_mul_f32_e64 v52, |v94|, -2.0
	v_mul_f32_e32 v52, 0x3fb8aa3b, v52
	v_exp_f32_e32 v96, v52
	v_mul_f32_e64 v52, |v95|, -2.0
	v_mul_f32_e32 v52, 0x3fb8aa3b, v52
	v_exp_f32_e32 v97, v52
	v_add_f32_e32 v79, 1.0, v96
	v_cndmask_b32_e64 v52, v84, -v84, vcc
	v_rcp_f32_e32 v84, v79
	v_add_f32_e32 v79, 1.0, v97
	v_rcp_f32_e32 v85, v79
	v_pk_add_f32 v[96:97], v[96:97], 1.0 op_sel_hi:[1,0] neg_lo:[1,0] neg_hi:[1,0]
	v_cmp_gt_f32_e32 vcc, 0, v95
	v_pk_add_f32 v[52:53], v[52:53], 1.0 op_sel_hi:[1,0]
	v_pk_mul_f32 v[84:85], v[96:97], v[84:85]
	v_pk_mul_f32 v[88:89], v[86:87], v[52:53]
	v_cndmask_b32_e64 v85, v85, -v85, vcc
	v_cmp_gt_f32_e32 vcc, 0, v94
	s_nop 1
	v_cndmask_b32_e64 v84, v84, -v84, vcc
	v_pk_add_f32 v[84:85], v[84:85], 1.0 op_sel_hi:[1,0]
	s_nop 0
	v_pk_mul_f32 v[94:95], v[90:91], v[84:85]
	s_nop 0
	v_add_f32_e32 v79, 0, v94
	v_add_f32_e32 v79, v95, v79
	v_add_f32_e32 v79, v88, v79
	v_add_f32_e32 v79, v89, v79
	v_add_f32_e32 v79, v92, v79
	v_add_f32_e32 v79, v93, v79
	v_add_f32_e32 v79, v80, v79
	v_add_f32_e32 v79, v81, v79
	ds_bpermute_b32 v80, v73, v79
	s_waitcnt lgkmcnt(0)
	v_add_f32_e32 v79, v79, v80
	ds_bpermute_b32 v80, v74, v79
	s_waitcnt lgkmcnt(0)
	v_add_f32_e32 v79, v79, v80
	ds_bpermute_b32 v80, v75, v79
	s_waitcnt lgkmcnt(0)
	v_add_f32_e32 v79, v79, v80
	ds_bpermute_b32 v80, v76, v79
	s_waitcnt lgkmcnt(0)
	v_add_f32_e32 v79, v79, v80
	ds_bpermute_b32 v80, v77, v79
	s_waitcnt lgkmcnt(0)
	v_add_f32_e32 v79, v79, v80
	ds_bpermute_b32 v80, v78, v79
	s_waitcnt lgkmcnt(0)
	v_add_f32_e32 v79, v79, v80
	v_mul_f32_e32 v80, 0x3b000000, v79
	v_pk_fma_f32 v[84:85], v[90:91], v[84:85], v[80:81] op_sel_hi:[1,1,0] neg_lo:[0,0,1] neg_hi:[0,0,1]
	v_pk_fma_f32 v[52:53], v[86:87], v[52:53], v[80:81] op_sel_hi:[1,1,0] neg_lo:[0,0,1] neg_hi:[0,0,1]
	v_pk_mul_f32 v[88:89], v[84:85], v[84:85]
	v_pk_mul_f32 v[86:87], v[52:53], v[52:53]
	v_add_f32_e32 v79, v88, v89
	v_pk_fma_f32 v[70:71], v[82:83], v[70:71], v[80:81] op_sel_hi:[1,1,0] neg_lo:[0,0,1] neg_hi:[0,0,1]
	v_add_f32_e32 v79, v86, v79
	v_pk_mul_f32 v[82:83], v[70:71], v[70:71]
	v_add_f32_e32 v79, v87, v79
	v_pk_fma_f32 v[54:55], v[68:69], v[54:55], v[80:81] op_sel_hi:[1,1,0] neg_lo:[0,0,1] neg_hi:[0,0,1]
	v_add_f32_e32 v79, v82, v79
	v_pk_mul_f32 v[68:69], v[54:55], v[54:55]
	v_add_f32_e32 v79, v83, v79
	v_add_f32_e32 v68, v68, v79
	v_add_f32_e32 v68, v69, v68
	ds_bpermute_b32 v69, v73, v68
	s_waitcnt lgkmcnt(0)
	v_add_f32_e32 v68, v68, v69
	ds_bpermute_b32 v69, v74, v68
	s_waitcnt lgkmcnt(0)
	v_add_f32_e32 v68, v68, v69
	ds_bpermute_b32 v69, v75, v68
	s_waitcnt lgkmcnt(0)
	v_add_f32_e32 v68, v68, v69
	ds_bpermute_b32 v69, v76, v68
	s_waitcnt lgkmcnt(0)
	v_add_f32_e32 v68, v68, v69
	ds_bpermute_b32 v69, v77, v68
	s_waitcnt lgkmcnt(0)
	v_add_f32_e32 v68, v68, v69
	ds_bpermute_b32 v69, v78, v68
	s_waitcnt lgkmcnt(0)
	v_add_f32_e32 v68, v68, v69
	v_fmamk_f32 v68, v68, 0x3b000000, v225
	v_mul_f32_e32 v69, 0x4b800000, v68
	v_cmp_gt_f32_e32 vcc, s1, v68
	s_nop 1
	v_cndmask_b32_e32 v68, v68, v69, vcc
	v_rsq_f32_e32 v68, v68
	s_nop 0
	v_mul_f32_e32 v69, 0x45800000, v68
	v_cndmask_b32_e32 v68, v68, v69, vcc
	v_pk_mul_f32 v[52:53], v[52:53], v[68:69] op_sel_hi:[1,0]
	v_pk_mul_f32 v[80:81], v[84:85], v[68:69] op_sel_hi:[1,0]
	v_pk_fma_f32 v[82:83], v[10:11], v[52:53], v[14:15]
	v_pk_mul_f32 v[52:53], v[70:71], v[68:69] op_sel_hi:[1,0]
	v_pk_fma_f32 v[80:81], v[8:9], v[80:81], v[12:13]
	v_pk_fma_f32 v[70:71], v[0:1], v[52:53], v[4:5]
	v_pk_mul_f32 v[52:53], v[54:55], v[68:69] op_sel_hi:[1,0]
	v_cvt_pk_bf16_f32 v54, v70, v71
	v_pk_fma_f32 v[68:69], v[2:3], v[52:53], v[6:7]
	v_cvt_pk_bf16_f32 v52, v80, v81
	v_cvt_pk_bf16_f32 v53, v82, v83
	v_cvt_pk_bf16_f32 v55, v68, v69
	global_store_dwordx4 v[66:67], v[52:55], off
	s_and_saveexec_b64 s[12:13], s[4:5]
	s_cbranch_execz .LBB0_162
	v_lshlrev_b32_e32 v52, 16, v48
	v_and_b32_e32 v53, 0xffff0000, v48
	v_pk_mul_f32 v[54:55], v[52:53], v[52:53]
	v_lshlrev_b32_e32 v48, 16, v49
	v_and_b32_e32 v49, 0xffff0000, v49
	v_pk_mul_f32 v[66:67], v[48:49], v[48:49]
	v_add_f32_e32 v54, v54, v55
	v_lshlrev_b32_e32 v68, 16, v50
	v_and_b32_e32 v69, 0xffff0000, v50
	v_add_f32_e32 v54, v66, v54
	v_pk_mul_f32 v[70:71], v[68:69], v[68:69]
	v_add_f32_e32 v54, v67, v54
	v_lshlrev_b32_e32 v50, 16, v51
	v_and_b32_e32 v51, 0xffff0000, v51
	v_add_f32_e32 v54, v70, v54
	v_pk_mul_f32 v[80:81], v[50:51], v[50:51]
	v_add_f32_e32 v54, v71, v54
	v_lshlrev_b32_e32 v82, 16, v44
	v_and_b32_e32 v83, 0xffff0000, v44
	v_add_f32_e32 v54, v80, v54
	v_pk_mul_f32 v[84:85], v[82:83], v[82:83]
	v_add_f32_e32 v54, v81, v54
	v_lshlrev_b32_e32 v86, 16, v45
	v_and_b32_e32 v87, 0xffff0000, v45
	v_add_f32_e32 v54, v84, v54
	v_pk_mul_f32 v[44:45], v[86:87], v[86:87]
	v_add_f32_e32 v54, v85, v54
	v_lshlrev_b32_e32 v88, 16, v46
	v_and_b32_e32 v89, 0xffff0000, v46
	v_add_f32_e32 v44, v44, v54
	v_pk_mul_f32 v[90:91], v[88:89], v[88:89]
	v_add_f32_e32 v44, v45, v44
	v_lshlrev_b32_e32 v92, 16, v47
	v_and_b32_e32 v93, 0xffff0000, v47
	v_add_f32_e32 v44, v90, v44
	v_pk_mul_f32 v[46:47], v[92:93], v[92:93]
	v_add_f32_e32 v44, v91, v44
	v_add_f32_e32 v44, v46, v44
	v_add_f32_e32 v44, v47, v44
	ds_bpermute_b32 v45, v73, v44
	s_mov_b32 s9, 0x800000
	s_mul_hi_i32 s1, s0, 0x38e38e39
	s_lshr_b32 s8, s1, 31
	s_ashr_i32 s1, s1, 9
	s_waitcnt lgkmcnt(0)
	v_add_f32_e32 v44, v44, v45
	ds_bpermute_b32 v45, v74, v44
	s_add_i32 s1, s1, s8
	s_mulk_i32 s1, 0x900
	s_sub_i32 s1, s0, s1
	s_cmpk_gt_i32 s1, 0xff
	s_waitcnt lgkmcnt(0)
	v_add_f32_e32 v44, v44, v45
	ds_bpermute_b32 v45, v75, v44
	s_waitcnt lgkmcnt(0)
	v_add_f32_e32 v44, v44, v45
	v_fmamk_f32 v44, v44, 0x3c000000, v225
	v_mul_f32_e32 v45, 0x4b800000, v44
	v_cmp_gt_f32_e32 vcc, s9, v44
	s_nop 1
	v_cndmask_b32_e32 v44, v44, v45, vcc
	v_rsq_f32_e32 v44, v44
	s_nop 0
	v_mul_f32_e32 v45, 0x45800000, v44
	v_cndmask_b32_e32 v70, v44, v45, vcc
	v_pk_mul_f32 v[44:45], v[70:71], v[52:53] op_sel_hi:[0,1]
	v_pk_mul_f32 v[52:53], v[28:29], v[44:45]
	v_pk_mul_f32 v[44:45], v[70:71], v[48:49] op_sel_hi:[0,1]
	v_pk_mul_f32 v[54:55], v[30:31], v[44:45]
	v_pk_mul_f32 v[44:45], v[70:71], v[68:69] op_sel_hi:[0,1]
	s_cselect_b64 vcc, -1, 0
	s_add_i32 s8, s1, 0xffffff00
	v_pk_mul_f32 v[66:67], v[24:25], v[44:45]
	v_pk_mul_f32 v[44:45], v[70:71], v[50:51] op_sel_hi:[0,1]
	v_pk_mul_f32 v[48:49], v[70:71], v[88:89] op_sel_hi:[0,1]
	s_and_b32 s9, s1, 63
	s_ashr_i32 s8, s8, 6
	v_pk_mul_f32 v[68:69], v[26:27], v[44:45]
	v_pk_mul_f32 v[44:45], v[70:71], v[82:83] op_sel_hi:[0,1]
	v_pk_mul_f32 v[46:47], v[70:71], v[86:87] op_sel_hi:[0,1]
	v_pk_mul_f32 v[50:51], v[16:17], v[48:49]
	v_pk_mul_f32 v[48:49], v[70:71], v[92:93] op_sel_hi:[0,1]
	v_mov_b32_e32 v70, s9
	v_mov_b32_e32 v71, s8
	v_cndmask_b32_e64 v70, v70, v71, s[6:7]
	ds_bpermute_b32 v80, v74, v52
	ds_bpermute_b32 v79, v74, v53
	v_lshlrev_b32_e32 v70, 5, v70
	v_cndmask_b32_e32 v70, 0, v70, vcc
	v_ashrrev_i32_e32 v71, 31, v70
	v_pk_mul_f32 v[44:45], v[20:21], v[44:45]
	v_pk_mul_f32 v[46:47], v[22:23], v[46:47]
	v_pk_mul_f32 v[48:49], v[18:19], v[48:49]
	s_cmpk_lt_i32 s1, 0x100
	v_lshl_add_u64 v[70:71], v[70:71], 3, v[58:59]
	global_load_dwordx4 v[100:103], v[70:71], off
	global_load_dwordx4 v[104:107], v[70:71], off offset:16
	global_load_dwordx4 v[108:111], v[70:71], off offset:32
	global_load_dwordx4 v[112:115], v[70:71], off offset:48
	global_load_dwordx4 v[116:119], v[70:71], off offset:64
	global_load_dwordx4 v[120:123], v[70:71], off offset:80
	global_load_dwordx4 v[124:127], v[70:71], off offset:96
	global_load_dwordx4 v[128:131], v[70:71], off offset:112
	s_waitcnt vmcnt(0)
	s_cbranch_scc1 .LBB0_147
	s_waitcnt lgkmcnt(1)
	v_mul_f32_e32 v86, v72, v80
	s_waitcnt lgkmcnt(0)
	v_mul_f32_e32 v81, v72, v79
	v_mov_b32_e32 v80, v53
	s_waitcnt vmcnt(0)
	v_pk_mul_f32 v[80:81], v[80:81], v[102:103]
	v_mul_f32_e32 v52, v52, v100
	v_mul_f32_e32 v82, v86, v101
	v_mov_b32_e32 v53, v81
	v_mov_b32_e32 v83, v80
	v_pk_add_f32 v[52:53], v[52:53], v[82:83]
.LBB0_147:
	s_waitcnt lgkmcnt(1)
	ds_bpermute_b32 v80, v74, v54
	s_waitcnt lgkmcnt(1)
	ds_bpermute_b32 v79, v74, v55
	v_cndmask_b32_e64 v81, 0, 1, vcc
	v_cmp_ne_u32_e64 s[8:9], 1, v81
	s_andn2_b64 vcc, exec, vcc
	s_cbranch_vccnz .LBB0_149
	s_waitcnt lgkmcnt(1)
	v_mul_f32_e32 v86, v72, v80
	s_waitcnt lgkmcnt(0)
	v_mul_f32_e32 v81, v72, v79
	v_mov_b32_e32 v80, v55
	s_waitcnt vmcnt(0)
	v_pk_mul_f32 v[80:81], v[80:81], v[106:107]
	v_mul_f32_e32 v54, v54, v104
	v_mul_f32_e32 v82, v86, v105
	v_mov_b32_e32 v55, v81
	v_mov_b32_e32 v83, v80
	v_pk_add_f32 v[54:55], v[54:55], v[82:83]
.LBB0_149:
	s_waitcnt lgkmcnt(1)
	ds_bpermute_b32 v80, v74, v66
	s_waitcnt lgkmcnt(1)
	ds_bpermute_b32 v79, v74, v67
	s_and_b64 vcc, exec, s[8:9]
	s_cbranch_vccnz .LBB0_151
	s_waitcnt lgkmcnt(1)
	v_mul_f32_e32 v86, v72, v80
	s_waitcnt lgkmcnt(0)
	v_mul_f32_e32 v81, v72, v79
	v_mov_b32_e32 v80, v67
	s_waitcnt vmcnt(0)
	v_pk_mul_f32 v[80:81], v[80:81], v[110:111]
	v_mul_f32_e32 v66, v66, v108
	v_mul_f32_e32 v82, v86, v109
	v_mov_b32_e32 v67, v81
	v_mov_b32_e32 v83, v80
	v_pk_add_f32 v[66:67], v[66:67], v[82:83]
.LBB0_151:
	s_waitcnt lgkmcnt(1)
	ds_bpermute_b32 v80, v74, v68
	s_waitcnt lgkmcnt(1)
	ds_bpermute_b32 v79, v74, v69
	s_and_b64 vcc, exec, s[8:9]
	s_cbranch_vccnz .LBB0_153
	s_waitcnt lgkmcnt(1)
	v_mul_f32_e32 v86, v72, v80
	s_waitcnt lgkmcnt(0)
	v_mul_f32_e32 v81, v72, v79
	v_mov_b32_e32 v80, v69
	s_waitcnt vmcnt(0)
	v_pk_mul_f32 v[80:81], v[80:81], v[114:115]
	v_mul_f32_e32 v68, v68, v112
	v_mul_f32_e32 v82, v86, v113
	v_mov_b32_e32 v69, v81
	v_mov_b32_e32 v83, v80
	v_pk_add_f32 v[68:69], v[68:69], v[82:83]
.LBB0_153:
	s_waitcnt lgkmcnt(1)
	ds_bpermute_b32 v80, v74, v44
	s_waitcnt lgkmcnt(1)
	ds_bpermute_b32 v79, v74, v45
	s_and_b64 vcc, exec, s[8:9]
	s_cbranch_vccnz .LBB0_155
	s_waitcnt lgkmcnt(1)
	v_mul_f32_e32 v86, v72, v80
	s_waitcnt lgkmcnt(0)
	v_mul_f32_e32 v81, v72, v79
	v_mov_b32_e32 v80, v45
	s_waitcnt vmcnt(0)
	v_pk_mul_f32 v[80:81], v[80:81], v[118:119]
	v_mul_f32_e32 v44, v44, v116
	v_mul_f32_e32 v82, v86, v117
	v_mov_b32_e32 v45, v81
	v_mov_b32_e32 v83, v80
	v_pk_add_f32 v[44:45], v[44:45], v[82:83]
.LBB0_155:
	s_waitcnt lgkmcnt(1)
	ds_bpermute_b32 v80, v74, v46
	s_waitcnt lgkmcnt(1)
	ds_bpermute_b32 v79, v74, v47
	s_and_b64 vcc, exec, s[8:9]
	s_cbranch_vccnz .LBB0_157
	s_waitcnt lgkmcnt(1)
	v_mul_f32_e32 v86, v72, v80
	s_waitcnt lgkmcnt(0)
	v_mul_f32_e32 v81, v72, v79
	v_mov_b32_e32 v80, v47
	s_waitcnt vmcnt(0)
	v_pk_mul_f32 v[80:81], v[80:81], v[122:123]
	v_mul_f32_e32 v46, v46, v120
	v_mul_f32_e32 v82, v86, v121
	v_mov_b32_e32 v47, v81
	v_mov_b32_e32 v83, v80
	v_pk_add_f32 v[46:47], v[46:47], v[82:83]
.LBB0_157:
	s_waitcnt lgkmcnt(1)
	ds_bpermute_b32 v80, v74, v50
	s_waitcnt lgkmcnt(1)
	ds_bpermute_b32 v79, v74, v51
	s_and_b64 vcc, exec, s[8:9]
	s_cbranch_vccnz .LBB0_159
	s_waitcnt lgkmcnt(1)
	v_mul_f32_e32 v86, v72, v80
	s_waitcnt lgkmcnt(0)
	v_mul_f32_e32 v81, v72, v79
	v_mov_b32_e32 v80, v51
	s_waitcnt vmcnt(0)
	v_pk_mul_f32 v[80:81], v[80:81], v[126:127]
	v_mul_f32_e32 v50, v50, v124
	v_mul_f32_e32 v82, v86, v125
	v_mov_b32_e32 v51, v81
	v_mov_b32_e32 v83, v80
	v_pk_add_f32 v[50:51], v[50:51], v[82:83]
.LBB0_159:
	s_waitcnt lgkmcnt(1)
	ds_bpermute_b32 v80, v74, v48
	s_waitcnt lgkmcnt(1)
	ds_bpermute_b32 v79, v74, v49
	s_and_b64 vcc, exec, s[8:9]
	s_cbranch_vccnz .LBB0_161
	s_waitcnt lgkmcnt(0)
	v_mul_f32_e32 v71, v72, v79
	v_mov_b32_e32 v70, v49
	v_mul_f32_e32 v80, v72, v80
	s_waitcnt vmcnt(0)
	v_pk_mul_f32 v[70:71], v[70:71], v[130:131]
	v_mul_f32_e32 v48, v48, v128
	v_mul_f32_e32 v80, v80, v129
	v_mov_b32_e32 v49, v71
	v_mov_b32_e32 v81, v70
	v_pk_add_f32 v[48:49], v[48:49], v[80:81]

.LBB0_162:
	s_or_b64 exec, exec, s[12:13]
	s_waitcnt vmcnt(1)
	v_lshlrev_b32_e32 v46, 16, v43
	v_and_b32_e32 v47, 0xffff0000, v43
	s_mov_b32 s8, 0x3d372713
	v_pk_mul_f32 v[48:49], v[46:47], s[8:9] op_sel_hi:[1,0]
	s_mov_b32 s12, 0x3f4c422a
	v_pk_mul_f32 v[48:49], v[48:49], v[46:47]
	s_mov_b32 s1, 0x800000
	v_pk_fma_f32 v[48:49], v[48:49], v[46:47], v[46:47]
	v_pk_mul_f32 v[46:47], v[46:47], 0.5 op_sel_hi:[1,0]
	v_pk_mul_f32 v[48:49], v[48:49], s[12:13] op_sel_hi:[1,0]
	v_lshl_add_u64 v[44:45], s[2:3], 0, v[192:193]
	v_mul_f32_e64 v43, |v48|, -2.0
	v_mul_f32_e32 v43, 0x3fb8aa3b, v43
	v_exp_f32_e32 v50, v43
	v_mul_f32_e64 v43, |v49|, -2.0
	v_mul_f32_e32 v43, 0x3fb8aa3b, v43
	v_exp_f32_e32 v51, v43
	v_add_f32_e32 v43, 1.0, v50
	v_rcp_f32_e32 v52, v43
	v_cmp_gt_f32_e32 vcc, 0, v49
	v_add_f32_e32 v43, 1.0, v51
	v_rcp_f32_e32 v53, v43
	v_pk_add_f32 v[50:51], v[50:51], 1.0 op_sel_hi:[1,0] neg_lo:[1,0] neg_hi:[1,0]
	s_nop 0
	v_pk_mul_f32 v[50:51], v[50:51], v[52:53]
	v_lshlrev_b32_e32 v52, 16, v42
	v_and_b32_e32 v53, 0xffff0000, v42
	v_pk_mul_f32 v[54:55], v[52:53], s[8:9] op_sel_hi:[1,0]
	v_cndmask_b32_e64 v43, v51, -v51, vcc
	v_pk_mul_f32 v[54:55], v[54:55], v[52:53]
	v_cmp_gt_f32_e32 vcc, 0, v48
	v_pk_fma_f32 v[54:55], v[54:55], v[52:53], v[52:53]
	v_pk_mul_f32 v[52:53], v[52:53], 0.5 op_sel_hi:[1,0]
	v_pk_mul_f32 v[54:55], v[54:55], s[12:13] op_sel_hi:[1,0]
	s_nop 0
	v_mul_f32_e64 v42, |v54|, -2.0
	v_mul_f32_e32 v42, 0x3fb8aa3b, v42
	v_exp_f32_e32 v64, v42
	v_mul_f32_e64 v42, |v55|, -2.0
	v_mul_f32_e32 v42, 0x3fb8aa3b, v42
	v_exp_f32_e32 v65, v42
	v_add_f32_e32 v48, 1.0, v64
	v_rcp_f32_e32 v48, v48
	v_cndmask_b32_e64 v42, v50, -v50, vcc
	v_add_f32_e32 v49, 1.0, v65
	v_rcp_f32_e32 v49, v49
	v_pk_add_f32 v[64:65], v[64:65], 1.0 op_sel_hi:[1,0] neg_lo:[1,0] neg_hi:[1,0]
	v_cmp_gt_f32_e32 vcc, 0, v55
	v_pk_add_f32 v[42:43], v[42:43], 1.0 op_sel_hi:[1,0]
	v_pk_mul_f32 v[48:49], v[64:65], v[48:49]
	v_lshlrev_b32_e32 v64, 16, v41
	v_and_b32_e32 v65, 0xffff0000, v41
	v_pk_mul_f32 v[66:67], v[64:65], s[8:9] op_sel_hi:[1,0]
	v_cndmask_b32_e64 v49, v49, -v49, vcc
	v_pk_mul_f32 v[66:67], v[66:67], v[64:65]
	v_cmp_gt_f32_e32 vcc, 0, v54
	v_pk_fma_f32 v[66:67], v[66:67], v[64:65], v[64:65]
	v_pk_mul_f32 v[64:65], v[64:65], 0.5 op_sel_hi:[1,0]
	v_pk_mul_f32 v[66:67], v[66:67], s[12:13] op_sel_hi:[1,0]
	v_cndmask_b32_e64 v48, v48, -v48, vcc
	v_mul_f32_e64 v41, |v66|, -2.0
	v_mul_f32_e32 v41, 0x3fb8aa3b, v41
	v_exp_f32_e32 v68, v41
	v_mul_f32_e64 v41, |v67|, -2.0
	v_mul_f32_e32 v41, 0x3fb8aa3b, v41
	v_exp_f32_e32 v69, v41
	v_add_f32_e32 v41, 1.0, v68
	v_rcp_f32_e32 v54, v41
	v_cmp_gt_f32_e32 vcc, 0, v67
	v_add_f32_e32 v41, 1.0, v69
	v_rcp_f32_e32 v55, v41
	v_pk_add_f32 v[68:69], v[68:69], 1.0 op_sel_hi:[1,0] neg_lo:[1,0] neg_hi:[1,0]
	v_pk_add_f32 v[48:49], v[48:49], 1.0 op_sel_hi:[1,0]
	v_pk_mul_f32 v[50:51], v[46:47], v[42:43]
	v_pk_mul_f32 v[54:55], v[68:69], v[54:55]
	v_lshlrev_b32_e32 v68, 16, v40
	v_and_b32_e32 v69, 0xffff0000, v40
	s_waitcnt lgkmcnt(1)
	v_pk_mul_f32 v[80:81], v[68:69], s[8:9] op_sel_hi:[1,0]
	v_cndmask_b32_e64 v41, v55, -v55, vcc
	v_pk_mul_f32 v[80:81], v[80:81], v[68:69]
	v_cmp_gt_f32_e32 vcc, 0, v66
	v_pk_fma_f32 v[80:81], v[80:81], v[68:69], v[68:69]
	v_pk_mul_f32 v[68:69], v[68:69], 0.5 op_sel_hi:[1,0]
	v_pk_mul_f32 v[80:81], v[80:81], s[12:13] op_sel_hi:[1,0]
	v_pk_mul_f32 v[70:71], v[52:53], v[48:49]
	v_mul_f32_e64 v40, |v80|, -2.0
	v_mul_f32_e32 v40, 0x3fb8aa3b, v40
	v_exp_f32_e32 v82, v40
	v_mul_f32_e64 v40, |v81|, -2.0
	v_mul_f32_e32 v40, 0x3fb8aa3b, v40
	v_exp_f32_e32 v83, v40
	v_cndmask_b32_e64 v40, v54, -v54, vcc
	v_add_f32_e32 v54, 1.0, v82
	v_rcp_f32_e32 v54, v54
	v_add_f32_e32 v55, 1.0, v83
	v_rcp_f32_e32 v55, v55
	v_pk_add_f32 v[82:83], v[82:83], 1.0 op_sel_hi:[1,0] neg_lo:[1,0] neg_hi:[1,0]
	v_cmp_gt_f32_e32 vcc, 0, v81
	v_pk_add_f32 v[40:41], v[40:41], 1.0 op_sel_hi:[1,0]
	v_pk_mul_f32 v[54:55], v[82:83], v[54:55]
	v_pk_mul_f32 v[66:67], v[64:65], v[40:41]
	v_cndmask_b32_e64 v55, v55, -v55, vcc
	v_cmp_gt_f32_e32 vcc, 0, v80
	s_nop 1
	v_cndmask_b32_e64 v54, v54, -v54, vcc
	v_pk_add_f32 v[54:55], v[54:55], 1.0 op_sel_hi:[1,0]
	s_nop 0
	v_pk_mul_f32 v[80:81], v[68:69], v[54:55]
	s_waitcnt lgkmcnt(0)
	v_add_f32_e32 v79, 0, v80
	v_add_f32_e32 v79, v81, v79
	v_add_f32_e32 v66, v66, v79
	v_add_f32_e32 v66, v67, v66
	v_add_f32_e32 v66, v70, v66
	v_add_f32_e32 v66, v71, v66
	v_add_f32_e32 v50, v50, v66
	v_add_f32_e32 v50, v51, v50
	ds_bpermute_b32 v51, v73, v50
	s_waitcnt lgkmcnt(0)
	v_add_f32_e32 v50, v50, v51
	ds_bpermute_b32 v51, v74, v50
	s_waitcnt lgkmcnt(0)
	v_add_f32_e32 v50, v50, v51
	ds_bpermute_b32 v51, v75, v50
	s_waitcnt lgkmcnt(0)
	v_add_f32_e32 v50, v50, v51
	ds_bpermute_b32 v51, v76, v50
	s_waitcnt lgkmcnt(0)
	v_add_f32_e32 v50, v50, v51
	ds_bpermute_b32 v51, v77, v50
	s_waitcnt lgkmcnt(0)
	v_add_f32_e32 v50, v50, v51
	ds_bpermute_b32 v51, v78, v50
	s_waitcnt lgkmcnt(0)
	v_add_f32_e32 v50, v50, v51
	v_mul_f32_e32 v50, 0x3b000000, v50
	v_pk_fma_f32 v[54:55], v[68:69], v[54:55], v[50:51] op_sel_hi:[1,1,0] neg_lo:[0,0,1] neg_hi:[0,0,1]
	v_pk_fma_f32 v[40:41], v[64:65], v[40:41], v[50:51] op_sel_hi:[1,1,0] neg_lo:[0,0,1] neg_hi:[0,0,1]
	v_pk_mul_f32 v[66:67], v[54:55], v[54:55]
	v_pk_mul_f32 v[64:65], v[40:41], v[40:41]
	v_pk_fma_f32 v[48:49], v[52:53], v[48:49], v[50:51] op_sel_hi:[1,1,0] neg_lo:[0,0,1] neg_hi:[0,0,1]
	v_pk_fma_f32 v[42:43], v[46:47], v[42:43], v[50:51] op_sel_hi:[1,1,0] neg_lo:[0,0,1] neg_hi:[0,0,1]
	v_add_f32_e32 v50, v66, v67
	v_add_f32_e32 v50, v64, v50
	v_pk_mul_f32 v[52:53], v[48:49], v[48:49]
	v_add_f32_e32 v50, v65, v50
	v_add_f32_e32 v50, v52, v50
	v_pk_mul_f32 v[46:47], v[42:43], v[42:43]
	v_add_f32_e32 v50, v53, v50
	v_add_f32_e32 v46, v46, v50
	v_add_f32_e32 v46, v47, v46
	ds_bpermute_b32 v47, v73, v46
	s_waitcnt lgkmcnt(0)
	v_add_f32_e32 v46, v46, v47
	ds_bpermute_b32 v47, v74, v46
	s_waitcnt lgkmcnt(0)
	v_add_f32_e32 v46, v46, v47
	ds_bpermute_b32 v47, v75, v46
	s_waitcnt lgkmcnt(0)
	v_add_f32_e32 v46, v46, v47
	ds_bpermute_b32 v47, v76, v46
	s_waitcnt lgkmcnt(0)
	v_add_f32_e32 v46, v46, v47
	ds_bpermute_b32 v47, v77, v46
	s_waitcnt lgkmcnt(0)
	v_add_f32_e32 v46, v46, v47
	ds_bpermute_b32 v47, v78, v46
	s_waitcnt lgkmcnt(0)
	v_add_f32_e32 v46, v46, v47
	v_fmamk_f32 v46, v46, 0x3b000000, v225
	v_mul_f32_e32 v47, 0x4b800000, v46
	v_cmp_gt_f32_e32 vcc, s1, v46
	s_nop 1
	v_cndmask_b32_e32 v46, v46, v47, vcc
	v_rsq_f32_e32 v46, v46
	s_nop 0
	v_mul_f32_e32 v47, 0x45800000, v46
	v_cndmask_b32_e32 v46, v46, v47, vcc
	v_pk_mul_f32 v[40:41], v[40:41], v[46:47] op_sel_hi:[1,0]
	v_pk_mul_f32 v[50:51], v[54:55], v[46:47] op_sel_hi:[1,0]
	v_pk_fma_f32 v[52:53], v[10:11], v[40:41], v[14:15]
	v_pk_mul_f32 v[40:41], v[48:49], v[46:47] op_sel_hi:[1,0]
	v_pk_fma_f32 v[50:51], v[8:9], v[50:51], v[12:13]
	v_pk_fma_f32 v[48:49], v[0:1], v[40:41], v[4:5]
	v_pk_mul_f32 v[40:41], v[42:43], v[46:47] op_sel_hi:[1,0]
	v_cvt_pk_bf16_f32 v42, v48, v49
	v_pk_fma_f32 v[46:47], v[2:3], v[40:41], v[6:7]
	v_cvt_pk_bf16_f32 v40, v50, v51
	v_cvt_pk_bf16_f32 v41, v52, v53
	v_cvt_pk_bf16_f32 v43, v46, v47
	global_store_dwordx4 v[44:45], v[40:43], off offset:1024
	s_and_saveexec_b64 s[12:13], s[4:5]
	s_cbranch_execz .LBB0_139
	v_lshlrev_b32_e32 v40, 16, v36
	v_and_b32_e32 v41, 0xffff0000, v36
	v_pk_mul_f32 v[42:43], v[40:41], v[40:41]
	v_lshlrev_b32_e32 v36, 16, v37
	v_and_b32_e32 v37, 0xffff0000, v37
	v_pk_mul_f32 v[44:45], v[36:37], v[36:37]
	v_add_f32_e32 v42, v42, v43
	v_lshlrev_b32_e32 v46, 16, v38
	v_and_b32_e32 v47, 0xffff0000, v38
	v_add_f32_e32 v42, v44, v42
	v_pk_mul_f32 v[48:49], v[46:47], v[46:47]
	v_add_f32_e32 v42, v45, v42
	v_lshlrev_b32_e32 v38, 16, v39
	v_and_b32_e32 v39, 0xffff0000, v39
	v_add_f32_e32 v42, v48, v42
	v_pk_mul_f32 v[50:51], v[38:39], v[38:39]
	v_add_f32_e32 v42, v49, v42
	v_lshlrev_b32_e32 v52, 16, v32
	v_and_b32_e32 v53, 0xffff0000, v32
	v_add_f32_e32 v42, v50, v42
	v_pk_mul_f32 v[54:55], v[52:53], v[52:53]
	v_add_f32_e32 v42, v51, v42
	v_lshlrev_b32_e32 v64, 16, v33
	v_and_b32_e32 v65, 0xffff0000, v33
	v_add_f32_e32 v42, v54, v42
	v_pk_mul_f32 v[32:33], v[64:65], v[64:65]
	v_add_f32_e32 v42, v55, v42
	v_lshlrev_b32_e32 v66, 16, v34
	v_and_b32_e32 v67, 0xffff0000, v34
	v_add_f32_e32 v32, v32, v42
	v_pk_mul_f32 v[68:69], v[66:67], v[66:67]
	v_add_f32_e32 v32, v33, v32
	v_lshlrev_b32_e32 v70, 16, v35
	v_and_b32_e32 v71, 0xffff0000, v35
	v_add_f32_e32 v32, v68, v32
	v_pk_mul_f32 v[34:35], v[70:71], v[70:71]
	v_add_f32_e32 v32, v69, v32
	v_add_f32_e32 v32, v34, v32
	v_add_f32_e32 v32, v35, v32
	ds_bpermute_b32 v33, v73, v32
	s_mov_b32 s9, 0x800000
	s_mul_hi_i32 s1, s10, 0x38e38e39
	s_lshr_b32 s8, s1, 31
	s_ashr_i32 s1, s1, 9
	s_waitcnt lgkmcnt(0)
	v_add_f32_e32 v32, v32, v33
	ds_bpermute_b32 v33, v74, v32
	s_add_i32 s1, s1, s8
	s_mulk_i32 s1, 0x900
	s_sub_i32 s1, s10, s1
	s_cmpk_gt_i32 s1, 0xff
	s_waitcnt lgkmcnt(0)
	v_add_f32_e32 v32, v32, v33
	ds_bpermute_b32 v33, v75, v32
	s_waitcnt lgkmcnt(0)
	v_add_f32_e32 v32, v32, v33
	v_fmamk_f32 v32, v32, 0x3c000000, v225
	v_mul_f32_e32 v33, 0x4b800000, v32
	v_cmp_gt_f32_e32 vcc, s9, v32
	s_nop 1
	v_cndmask_b32_e32 v32, v32, v33, vcc
	v_rsq_f32_e32 v32, v32
	s_nop 0
	v_mul_f32_e32 v33, 0x45800000, v32
	v_cndmask_b32_e32 v48, v32, v33, vcc
	v_pk_mul_f32 v[32:33], v[48:49], v[40:41] op_sel_hi:[0,1]
	v_pk_mul_f32 v[34:35], v[28:29], v[32:33]
	v_pk_mul_f32 v[32:33], v[48:49], v[36:37] op_sel_hi:[0,1]
	v_pk_mul_f32 v[42:43], v[30:31], v[32:33]
	v_pk_mul_f32 v[32:33], v[48:49], v[46:47] op_sel_hi:[0,1]
	s_cselect_b64 vcc, -1, 0
	s_add_i32 s8, s1, 0xffffff00
	v_pk_mul_f32 v[44:45], v[24:25], v[32:33]
	v_pk_mul_f32 v[32:33], v[48:49], v[38:39] op_sel_hi:[0,1]
	v_pk_mul_f32 v[38:39], v[48:49], v[66:67] op_sel_hi:[0,1]
	s_and_b32 s9, s1, 63
	s_ashr_i32 s8, s8, 6
	v_pk_mul_f32 v[46:47], v[26:27], v[32:33]
	v_pk_mul_f32 v[32:33], v[48:49], v[52:53] op_sel_hi:[0,1]
	v_pk_mul_f32 v[36:37], v[48:49], v[64:65] op_sel_hi:[0,1]
	v_pk_mul_f32 v[40:41], v[16:17], v[38:39]
	v_pk_mul_f32 v[38:39], v[48:49], v[70:71] op_sel_hi:[0,1]
	v_mov_b32_e32 v48, s9
	v_mov_b32_e32 v49, s8
	v_cndmask_b32_e64 v48, v48, v49, s[6:7]
	ds_bpermute_b32 v51, v74, v34
	ds_bpermute_b32 v50, v74, v35
	v_lshlrev_b32_e32 v48, 5, v48
	v_cndmask_b32_e32 v48, 0, v48, vcc
	v_ashrrev_i32_e32 v49, 31, v48
	v_pk_mul_f32 v[32:33], v[20:21], v[32:33]
	v_pk_mul_f32 v[36:37], v[22:23], v[36:37]
	v_pk_mul_f32 v[38:39], v[18:19], v[38:39]
	s_cmpk_lt_i32 s1, 0x100
	v_lshl_add_u64 v[48:49], v[48:49], 3, v[58:59]
	global_load_dwordx4 v[132:135], v[48:49], off
	global_load_dwordx4 v[136:139], v[48:49], off offset:16
	global_load_dwordx4 v[140:143], v[48:49], off offset:32
	global_load_dwordx4 v[144:147], v[48:49], off offset:48
	global_load_dwordx4 v[148:151], v[48:49], off offset:64
	global_load_dwordx4 v[152:155], v[48:49], off offset:80
	global_load_dwordx4 v[156:159], v[48:49], off offset:96
	global_load_dwordx4 v[160:163], v[48:49], off offset:112
	s_waitcnt vmcnt(0)
	s_cbranch_scc1 .LBB0_165
	s_waitcnt lgkmcnt(1)
	v_mul_f32_e32 v64, v72, v51
	s_waitcnt lgkmcnt(0)
	v_mul_f32_e32 v51, v72, v50
	v_mov_b32_e32 v50, v35
	s_waitcnt vmcnt(0)
	v_pk_mul_f32 v[50:51], v[50:51], v[134:135]
	v_mul_f32_e32 v34, v34, v132
	v_mul_f32_e32 v52, v64, v133
	v_mov_b32_e32 v35, v51
	v_mov_b32_e32 v53, v50
	v_pk_add_f32 v[34:35], v[34:35], v[52:53]
.LBB0_165:
	s_waitcnt lgkmcnt(1)
	ds_bpermute_b32 v51, v74, v42
	s_waitcnt lgkmcnt(1)
	ds_bpermute_b32 v50, v74, v43
	v_cndmask_b32_e64 v52, 0, 1, vcc
	v_cmp_ne_u32_e64 s[8:9], 1, v52
	s_andn2_b64 vcc, exec, vcc
	s_cbranch_vccnz .LBB0_167
	s_waitcnt lgkmcnt(1)
	v_mul_f32_e32 v64, v72, v51
	s_waitcnt lgkmcnt(0)
	v_mul_f32_e32 v51, v72, v50
	v_mov_b32_e32 v50, v43
	s_waitcnt vmcnt(0)
	v_pk_mul_f32 v[50:51], v[50:51], v[138:139]
	v_mul_f32_e32 v42, v42, v136
	v_mul_f32_e32 v52, v64, v137
	v_mov_b32_e32 v43, v51
	v_mov_b32_e32 v53, v50
	v_pk_add_f32 v[42:43], v[42:43], v[52:53]
.LBB0_167:
	s_waitcnt lgkmcnt(1)
	ds_bpermute_b32 v51, v74, v44
	s_waitcnt lgkmcnt(1)
	ds_bpermute_b32 v50, v74, v45
	s_and_b64 vcc, exec, s[8:9]
	s_cbranch_vccnz .LBB0_169
	s_waitcnt lgkmcnt(1)
	v_mul_f32_e32 v64, v72, v51
	s_waitcnt lgkmcnt(0)
	v_mul_f32_e32 v51, v72, v50
	v_mov_b32_e32 v50, v45
	s_waitcnt vmcnt(0)
	v_pk_mul_f32 v[50:51], v[50:51], v[142:143]
	v_mul_f32_e32 v44, v44, v140
	v_mul_f32_e32 v52, v64, v141
	v_mov_b32_e32 v45, v51
	v_mov_b32_e32 v53, v50
	v_pk_add_f32 v[44:45], v[44:45], v[52:53]
.LBB0_169:
	s_waitcnt lgkmcnt(1)
	ds_bpermute_b32 v51, v74, v46
	s_waitcnt lgkmcnt(1)
	ds_bpermute_b32 v50, v74, v47
	s_and_b64 vcc, exec, s[8:9]
	s_cbranch_vccnz .LBB0_171
	s_waitcnt lgkmcnt(1)
	v_mul_f32_e32 v64, v72, v51
	s_waitcnt lgkmcnt(0)
	v_mul_f32_e32 v51, v72, v50
	v_mov_b32_e32 v50, v47
	s_waitcnt vmcnt(0)
	v_pk_mul_f32 v[50:51], v[50:51], v[146:147]
	v_mul_f32_e32 v46, v46, v144
	v_mul_f32_e32 v52, v64, v145
	v_mov_b32_e32 v47, v51
	v_mov_b32_e32 v53, v50
	v_pk_add_f32 v[46:47], v[46:47], v[52:53]
.LBB0_171:
	s_waitcnt lgkmcnt(1)
	ds_bpermute_b32 v51, v74, v32
	s_waitcnt lgkmcnt(1)
	ds_bpermute_b32 v50, v74, v33
	s_and_b64 vcc, exec, s[8:9]
	s_cbranch_vccnz .LBB0_173
	s_waitcnt lgkmcnt(1)
	v_mul_f32_e32 v64, v72, v51
	s_waitcnt lgkmcnt(0)
	v_mul_f32_e32 v51, v72, v50
	v_mov_b32_e32 v50, v33
	s_waitcnt vmcnt(0)
	v_pk_mul_f32 v[50:51], v[50:51], v[150:151]
	v_mul_f32_e32 v32, v32, v148
	v_mul_f32_e32 v52, v64, v149
	v_mov_b32_e32 v33, v51
	v_mov_b32_e32 v53, v50
	v_pk_add_f32 v[32:33], v[32:33], v[52:53]
.LBB0_173:
	s_waitcnt lgkmcnt(1)
	ds_bpermute_b32 v51, v74, v36
	s_waitcnt lgkmcnt(1)
	ds_bpermute_b32 v50, v74, v37
	s_and_b64 vcc, exec, s[8:9]
	s_cbranch_vccnz .LBB0_175
	s_waitcnt lgkmcnt(1)
	v_mul_f32_e32 v64, v72, v51
	s_waitcnt lgkmcnt(0)
	v_mul_f32_e32 v51, v72, v50
	v_mov_b32_e32 v50, v37
	s_waitcnt vmcnt(0)
	v_pk_mul_f32 v[50:51], v[50:51], v[154:155]
	v_mul_f32_e32 v36, v36, v152
	v_mul_f32_e32 v52, v64, v153
	v_mov_b32_e32 v37, v51
	v_mov_b32_e32 v53, v50
	v_pk_add_f32 v[36:37], v[36:37], v[52:53]
.LBB0_175:
	s_waitcnt lgkmcnt(1)
	ds_bpermute_b32 v51, v74, v40
	s_waitcnt lgkmcnt(1)
	ds_bpermute_b32 v50, v74, v41
	s_and_b64 vcc, exec, s[8:9]
	s_cbranch_vccnz .LBB0_177
	s_waitcnt lgkmcnt(1)
	v_mul_f32_e32 v64, v72, v51
	s_waitcnt lgkmcnt(0)
	v_mul_f32_e32 v51, v72, v50
	v_mov_b32_e32 v50, v41
	s_waitcnt vmcnt(0)
	v_pk_mul_f32 v[50:51], v[50:51], v[158:159]
	v_mul_f32_e32 v40, v40, v156
	v_mul_f32_e32 v52, v64, v157
	v_mov_b32_e32 v41, v51
	v_mov_b32_e32 v53, v50
	v_pk_add_f32 v[40:41], v[40:41], v[52:53]
.LBB0_177:
	s_waitcnt lgkmcnt(1)
	ds_bpermute_b32 v51, v74, v38
	s_waitcnt lgkmcnt(1)
	ds_bpermute_b32 v50, v74, v39
	s_and_b64 vcc, exec, s[8:9]
	s_cbranch_vccnz .LBB0_138
	s_waitcnt lgkmcnt(0)
	v_mul_f32_e32 v49, v72, v50
	v_mov_b32_e32 v48, v39
	v_mul_f32_e32 v51, v72, v51
	s_waitcnt vmcnt(0)
	v_pk_mul_f32 v[48:49], v[48:49], v[162:163]
	v_mul_f32_e32 v38, v38, v160
	v_mul_f32_e32 v50, v51, v161
	v_mov_b32_e32 v39, v49
	v_mov_b32_e32 v51, v48
	v_pk_add_f32 v[38:39], v[38:39], v[50:51]
	s_branch .LBB0_138

.LBB0_332:
	s_or_b64 exec, exec, s[6:7]
	s_waitcnt lgkmcnt(0)
	s_lshl_b64 s[4:5], s[14:15], 11
	v_ashrrev_i32_e32 v64, 5, v177
	v_lshl_add_u32 v67, v64, 4, v179
	ds_read2_b32 v[70:71], v67 offset1:1
	ds_read2_b32 v[72:73], v67 offset0:2 offset1:3
	ds_read2_b32 v[74:75], v67 offset0:8 offset1:9
	ds_read2_b32 v[76:77], v67 offset0:10 offset1:11
	ds_read2_b32 v[78:79], v67 offset0:16 offset1:17
	ds_read2_b32 v[80:81], v67 offset0:18 offset1:19
	ds_read2_b32 v[82:83], v67 offset0:24 offset1:25
	ds_read2_b32 v[84:85], v67 offset0:26 offset1:27
	s_add_u32 s4, s10, s4
	s_addc_u32 s5, s11, s5
	s_add_u32 s4, s4, s18
	s_addc_u32 s5, s5, s19
	s_add_i32 s31, s31, 1
	v_readlane_b32 s6, v254, 41
	v_readlane_b32 s7, v254, 42
	v_and_b32_e32 v65, 31, v177
	v_lshlrev_b32_e32 v66, 8, v178
	v_lshl_add_u32 v66, v64, 10, v66
	v_lshl_add_u32 v66, v65, 1, v66
	v_add_u32_e32 v66, 0x11000, v66
	s_waitcnt lgkmcnt(0)
	v_rcp_f32_e32 v70, v70
	v_rcp_f32_e32 v71, v71
	v_rcp_f32_e32 v72, v72
	v_rcp_f32_e32 v73, v73
	v_rcp_f32_e32 v74, v74
	v_rcp_f32_e32 v75, v75
	v_rcp_f32_e32 v76, v76
	v_rcp_f32_e32 v77, v77
	v_rcp_f32_e32 v78, v78
	v_rcp_f32_e32 v79, v79
	v_rcp_f32_e32 v80, v80
	v_rcp_f32_e32 v81, v81
	v_rcp_f32_e32 v82, v82
	v_rcp_f32_e32 v83, v83
	v_rcp_f32_e32 v84, v84
	v_rcp_f32_e32 v85, v85
	s_nop 1
	v_mul_f32_e32 v0, v0, v70
	v_cvt_pk_bf16_f32 v0, v0, v193
	ds_write_b16 v66, v0 offset:0
	v_mul_f32_e32 v48, v48, v70
	v_cvt_pk_bf16_f32 v48, v48, v193
	ds_write_b16 v66, v48 offset:64
	v_mul_f32_e32 v32, v32, v70
	v_cvt_pk_bf16_f32 v32, v32, v193
	ds_write_b16 v66, v32 offset:128
	v_mul_f32_e32 v16, v16, v70
	v_cvt_pk_bf16_f32 v16, v16, v193
	ds_write_b16 v66, v16 offset:192
	v_mul_f32_e32 v1, v1, v71
	v_cvt_pk_bf16_f32 v1, v1, v193
	ds_write_b16 v66, v1 offset:256
	v_mul_f32_e32 v49, v49, v71
	v_cvt_pk_bf16_f32 v49, v49, v193
	ds_write_b16 v66, v49 offset:320
	v_mul_f32_e32 v33, v33, v71
	v_cvt_pk_bf16_f32 v33, v33, v193
	ds_write_b16 v66, v33 offset:384
	v_mul_f32_e32 v17, v17, v71
	v_cvt_pk_bf16_f32 v17, v17, v193
	ds_write_b16 v66, v17 offset:448
	s_waitcnt lgkmcnt(7)
	v_mul_f32_e32 v2, v2, v72
	v_cvt_pk_bf16_f32 v2, v2, v193
	ds_write_b16 v66, v2 offset:512
	v_mul_f32_e32 v50, v50, v72
	v_cvt_pk_bf16_f32 v50, v50, v193
	ds_write_b16 v66, v50 offset:576
	v_mul_f32_e32 v34, v34, v72
	v_cvt_pk_bf16_f32 v34, v34, v193
	ds_write_b16 v66, v34 offset:640
	v_mul_f32_e32 v18, v18, v72
	v_cvt_pk_bf16_f32 v18, v18, v193
	ds_write_b16 v66, v18 offset:704
	v_mul_f32_e32 v3, v3, v73
	v_cvt_pk_bf16_f32 v3, v3, v193
	ds_write_b16 v66, v3 offset:768
	v_mul_f32_e32 v51, v51, v73
	v_cvt_pk_bf16_f32 v51, v51, v193
	ds_write_b16 v66, v51 offset:832
	v_mul_f32_e32 v35, v35, v73
	v_cvt_pk_bf16_f32 v35, v35, v193
	ds_write_b16 v66, v35 offset:896
	v_mul_f32_e32 v19, v19, v73
	v_cvt_pk_bf16_f32 v19, v19, v193
	ds_write_b16 v66, v19 offset:960
	s_waitcnt lgkmcnt(7)
	v_mul_f32_e32 v4, v4, v74
	v_cvt_pk_bf16_f32 v4, v4, v193
	ds_write_b16 v66, v4 offset:2048
	v_mul_f32_e32 v52, v52, v74
	v_cvt_pk_bf16_f32 v52, v52, v193
	ds_write_b16 v66, v52 offset:2112
	v_mul_f32_e32 v36, v36, v74
	v_cvt_pk_bf16_f32 v36, v36, v193
	ds_write_b16 v66, v36 offset:2176
	v_mul_f32_e32 v20, v20, v74
	v_cvt_pk_bf16_f32 v20, v20, v193
	ds_write_b16 v66, v20 offset:2240
	v_mul_f32_e32 v5, v5, v75
	v_cvt_pk_bf16_f32 v5, v5, v193
	ds_write_b16 v66, v5 offset:2304
	v_mul_f32_e32 v53, v53, v75
	v_cvt_pk_bf16_f32 v53, v53, v193
	ds_write_b16 v66, v53 offset:2368
	v_mul_f32_e32 v37, v37, v75
	v_cvt_pk_bf16_f32 v37, v37, v193
	ds_write_b16 v66, v37 offset:2432
	v_mul_f32_e32 v21, v21, v75
	v_cvt_pk_bf16_f32 v21, v21, v193
	ds_write_b16 v66, v21 offset:2496
	s_waitcnt lgkmcnt(7)
	v_mul_f32_e32 v6, v6, v76
	v_cvt_pk_bf16_f32 v6, v6, v193
	ds_write_b16 v66, v6 offset:2560
	v_mul_f32_e32 v54, v54, v76
	v_cvt_pk_bf16_f32 v54, v54, v193
	ds_write_b16 v66, v54 offset:2624
	v_mul_f32_e32 v38, v38, v76
	v_cvt_pk_bf16_f32 v38, v38, v193
	ds_write_b16 v66, v38 offset:2688
	v_mul_f32_e32 v22, v22, v76
	v_cvt_pk_bf16_f32 v22, v22, v193
	ds_write_b16 v66, v22 offset:2752
	v_mul_f32_e32 v7, v7, v77
	v_cvt_pk_bf16_f32 v7, v7, v193
	ds_write_b16 v66, v7 offset:2816
	v_mul_f32_e32 v55, v55, v77
	v_cvt_pk_bf16_f32 v55, v55, v193
	ds_write_b16 v66, v55 offset:2880
	v_mul_f32_e32 v39, v39, v77
	v_cvt_pk_bf16_f32 v39, v39, v193
	ds_write_b16 v66, v39 offset:2944
	v_mul_f32_e32 v23, v23, v77
	v_cvt_pk_bf16_f32 v23, v23, v193
	ds_write_b16 v66, v23 offset:3008
	s_waitcnt lgkmcnt(7)
	v_mul_f32_e32 v8, v8, v78
	v_cvt_pk_bf16_f32 v8, v8, v193
	ds_write_b16 v66, v8 offset:4096
	v_mul_f32_e32 v56, v56, v78
	v_cvt_pk_bf16_f32 v56, v56, v193
	ds_write_b16 v66, v56 offset:4160
	v_mul_f32_e32 v40, v40, v78
	v_cvt_pk_bf16_f32 v40, v40, v193
	ds_write_b16 v66, v40 offset:4224
	v_mul_f32_e32 v24, v24, v78
	v_cvt_pk_bf16_f32 v24, v24, v193
	ds_write_b16 v66, v24 offset:4288
	v_mul_f32_e32 v9, v9, v79
	v_cvt_pk_bf16_f32 v9, v9, v193
	ds_write_b16 v66, v9 offset:4352
	v_mul_f32_e32 v57, v57, v79
	v_cvt_pk_bf16_f32 v57, v57, v193
	ds_write_b16 v66, v57 offset:4416
	v_mul_f32_e32 v41, v41, v79
	v_cvt_pk_bf16_f32 v41, v41, v193
	ds_write_b16 v66, v41 offset:4480
	v_mul_f32_e32 v25, v25, v79
	v_cvt_pk_bf16_f32 v25, v25, v193
	ds_write_b16 v66, v25 offset:4544
	s_waitcnt lgkmcnt(7)
	v_mul_f32_e32 v10, v10, v80
	v_cvt_pk_bf16_f32 v10, v10, v193
	ds_write_b16 v66, v10 offset:4608
	v_mul_f32_e32 v58, v58, v80
	v_cvt_pk_bf16_f32 v58, v58, v193
	ds_write_b16 v66, v58 offset:4672
	v_mul_f32_e32 v42, v42, v80
	v_cvt_pk_bf16_f32 v42, v42, v193
	ds_write_b16 v66, v42 offset:4736
	v_mul_f32_e32 v26, v26, v80
	v_cvt_pk_bf16_f32 v26, v26, v193
	ds_write_b16 v66, v26 offset:4800
	v_mul_f32_e32 v11, v11, v81
	v_cvt_pk_bf16_f32 v11, v11, v193
	ds_write_b16 v66, v11 offset:4864
	v_mul_f32_e32 v59, v59, v81
	v_cvt_pk_bf16_f32 v59, v59, v193
	ds_write_b16 v66, v59 offset:4928
	v_mul_f32_e32 v43, v43, v81
	v_cvt_pk_bf16_f32 v43, v43, v193
	ds_write_b16 v66, v43 offset:4992
	v_mul_f32_e32 v27, v27, v81
	v_cvt_pk_bf16_f32 v27, v27, v193
	ds_write_b16 v66, v27 offset:5056
	s_waitcnt lgkmcnt(7)
	v_mul_f32_e32 v12, v12, v82
	v_cvt_pk_bf16_f32 v12, v12, v193
	ds_write_b16 v66, v12 offset:6144
	v_mul_f32_e32 v60, v60, v82
	v_cvt_pk_bf16_f32 v60, v60, v193
	ds_write_b16 v66, v60 offset:6208
	v_mul_f32_e32 v44, v44, v82
	v_cvt_pk_bf16_f32 v44, v44, v193
	ds_write_b16 v66, v44 offset:6272
	v_mul_f32_e32 v28, v28, v82
	v_cvt_pk_bf16_f32 v28, v28, v193
	ds_write_b16 v66, v28 offset:6336
	v_mul_f32_e32 v13, v13, v83
	v_cvt_pk_bf16_f32 v13, v13, v193
	ds_write_b16 v66, v13 offset:6400
	v_mul_f32_e32 v61, v61, v83
	v_cvt_pk_bf16_f32 v61, v61, v193
	ds_write_b16 v66, v61 offset:6464
	v_mul_f32_e32 v45, v45, v83
	v_cvt_pk_bf16_f32 v45, v45, v193
	ds_write_b16 v66, v45 offset:6528
	v_mul_f32_e32 v29, v29, v83
	v_cvt_pk_bf16_f32 v29, v29, v193
	ds_write_b16 v66, v29 offset:6592
	s_waitcnt lgkmcnt(7)
	v_mul_f32_e32 v14, v14, v84
	v_cvt_pk_bf16_f32 v14, v14, v193
	ds_write_b16 v66, v14 offset:6656
	v_mul_f32_e32 v62, v62, v84
	v_cvt_pk_bf16_f32 v62, v62, v193
	ds_write_b16 v66, v62 offset:6720
	v_mul_f32_e32 v46, v46, v84
	v_cvt_pk_bf16_f32 v46, v46, v193
	ds_write_b16 v66, v46 offset:6784
	v_mul_f32_e32 v30, v30, v84
	v_cvt_pk_bf16_f32 v30, v30, v193
	ds_write_b16 v66, v30 offset:6848
	v_mul_f32_e32 v15, v15, v85
	v_cvt_pk_bf16_f32 v15, v15, v193
	ds_write_b16 v66, v15 offset:6912
	v_mul_f32_e32 v63, v63, v85
	v_cvt_pk_bf16_f32 v63, v63, v193
	ds_write_b16 v66, v63 offset:6976
	v_mul_f32_e32 v47, v47, v85
	v_cvt_pk_bf16_f32 v47, v47, v193
	ds_write_b16 v66, v47 offset:7040
	v_mul_f32_e32 v31, v31, v85
	v_cvt_pk_bf16_f32 v31, v31, v193
	ds_write_b16 v66, v31 offset:7104
	v_lshrrev_b32_e32 v64, 4, v177
	v_and_b32_e32 v65, 15, v177
	v_lshlrev_b32_e32 v66, 8, v178
	v_lshl_add_u32 v66, v64, 8, v66
	v_lshl_add_u32 v66, v65, 4, v66
	v_add_u32_e32 v66, 0x11000, v66
	v_add_u32_e32 v68, v178, v64
	v_mov_b32_e32 v69, 0
	v_lshlrev_b64 v[68:69], 11, v[68:69]
	v_lshl_add_u64 v[68:69], s[4:5], 0, v[68:69]
	v_lshlrev_b32_e32 v70, 4, v65
	v_mov_b32_e32 v71, 0
	v_lshl_add_u64 v[68:69], v[68:69], 0, v[70:71]
	s_waitcnt lgkmcnt(0)
	ds_read_b128 v[0:3], v66 offset:0
	ds_read_b128 v[4:7], v66 offset:1024
	ds_read_b128 v[8:11], v66 offset:2048
	ds_read_b128 v[12:15], v66 offset:3072
	ds_read_b128 v[16:19], v66 offset:4096
	ds_read_b128 v[20:23], v66 offset:5120
	ds_read_b128 v[24:27], v66 offset:6144
	ds_read_b128 v[28:31], v66 offset:7168
	s_waitcnt lgkmcnt(7)
	global_store_dwordx4 v[68:69], v[0:3], off offset:1024
	v_add_co_u32_e32 v68, vcc, 0x2000, v68
	s_nop 1
	v_addc_co_u32_e32 v69, vcc, 0, v69, vcc
	s_waitcnt lgkmcnt(6)
	global_store_dwordx4 v[68:69], v[4:7], off offset:1024
	v_add_co_u32_e32 v68, vcc, 0x2000, v68
	s_nop 1
	v_addc_co_u32_e32 v69, vcc, 0, v69, vcc
	s_waitcnt lgkmcnt(5)
	global_store_dwordx4 v[68:69], v[8:11], off offset:1024
	v_add_co_u32_e32 v68, vcc, 0x2000, v68
	s_nop 1
	v_addc_co_u32_e32 v69, vcc, 0, v69, vcc
	s_waitcnt lgkmcnt(4)
	global_store_dwordx4 v[68:69], v[12:15], off offset:1024
	v_add_co_u32_e32 v68, vcc, 0x2000, v68
	s_nop 1
	v_addc_co_u32_e32 v69, vcc, 0, v69, vcc
	s_waitcnt lgkmcnt(3)
	global_store_dwordx4 v[68:69], v[16:19], off offset:1024
	v_add_co_u32_e32 v68, vcc, 0x2000, v68
	s_nop 1
	v_addc_co_u32_e32 v69, vcc, 0, v69, vcc
	s_waitcnt lgkmcnt(2)
	global_store_dwordx4 v[68:69], v[20:23], off offset:1024
	v_add_co_u32_e32 v68, vcc, 0x2000, v68
	s_nop 1
	v_addc_co_u32_e32 v69, vcc, 0, v69, vcc
	s_waitcnt lgkmcnt(1)
	global_store_dwordx4 v[68:69], v[24:27], off offset:1024
	v_add_co_u32_e32 v68, vcc, 0x2000, v68
	s_nop 1
	v_addc_co_u32_e32 v69, vcc, 0, v69, vcc
	s_waitcnt lgkmcnt(0)
	global_store_dwordx4 v[68:69], v[28:31], off offset:1024
	s_branch .Lattn_epi_pad_end
	s_nop 0
	s_nop 0
	s_nop 0
	s_nop 0
	s_nop 0
	s_nop 0
	s_nop 0
	s_nop 0
	s_nop 0
	s_nop 0
	s_nop 0
	s_nop 0
	s_nop 0
	s_nop 0
	s_nop 0
	s_nop 0
	s_nop 0
	s_nop 0
	s_nop 0
	s_nop 0
	s_nop 0
	s_nop 0
	s_nop 0
	s_nop 0
	s_nop 0
	s_nop 0
	s_nop 0
	s_nop 0
	s_nop 0
	s_nop 0
	s_nop 0
	s_nop 0
	s_nop 0
	s_nop 0
	s_nop 0
	s_nop 0
	s_nop 0
	s_nop 0
	s_nop 0
	s_nop 0
	s_nop 0
	s_nop 0
	s_nop 0
	s_nop 0
	s_nop 0
	s_nop 0
	s_nop 0
	s_nop 0
	s_nop 0
	s_nop 0
	s_nop 0
	s_nop 0
	s_nop 0
	s_nop 0
	s_nop 0
	s_nop 0
	s_nop 0
	s_nop 0
	s_nop 0
	s_nop 0
	s_nop 0
	s_nop 0
	s_nop 0
	s_nop 0
	s_nop 0
	s_nop 0
	s_nop 0
	s_nop 0
	s_nop 0
	s_nop 0
	s_nop 0
	s_nop 0
	s_nop 0
.Lattn_epi_pad_end:
	s_mul_i32 s4, s31, s82
	s_add_i32 s14, s4, s6
	s_cmpk_lt_i32 s14, 0x480
	s_cbranch_scc0 .LBB0_358

.LBB0_416:
	s_mul_hi_i32 s5, s4, 0x38e38e39
	s_lshr_b32 s6, s5, 31
	s_ashr_i32 s5, s5, 9
	s_add_i32 s8, s5, s6
	s_mul_i32 s5, s8, 0xfffff700
	s_add_i32 s6, s4, s5
	s_cmpk_gt_i32 s6, 0xff
	s_cselect_b64 s[10:11], -1, 0
	s_and_b64 s[12:13], s[10:11], exec
	s_cselect_b32 s5, s8, 32
	s_cmp_eq_u32 s5, s18
	v_lshlrev_b32_e32 v86, 2, v80
	s_cbranch_scc1 .LBB0_418
	s_load_dwordx2 s[26:27], s[2:3], 0x28
	s_mul_i32 s9, s5, 0x6000
	s_mul_hi_i32 s7, s5, 0x6000
	s_waitcnt lgkmcnt(0)
	s_add_u32 s28, s26, 0x1000
	s_addc_u32 s29, s27, 0
	s_add_u32 s30, s37, s9
	s_addc_u32 s31, s40, s7
	s_add_u32 s34, s30, 0x1000
	s_addc_u32 s35, s31, 0
	s_add_u32 s24, s30, 0x18c000
	s_addc_u32 s25, s31, 0
	s_add_u32 s22, s30, 0x18d000
	s_addc_u32 s23, s31, 0
	s_add_u32 s20, s30, 0x318000
	s_addc_u32 s21, s31, 0
	s_add_u32 s18, s30, 0x319000
	s_addc_u32 s19, s31, 0
	s_add_u32 s14, s30, 0x4a4000
	s_addc_u32 s15, s31, 0
	s_add_u32 s12, s30, 0x4a5000
	s_addc_u32 s13, s31, 0
	global_load_dwordx4 v[108:111], v86, s[26:27]
	global_load_dwordx4 v[112:115], v86, s[28:29]
	global_load_dwordx4 v[116:119], v86, s[30:31]
	global_load_dwordx4 v[120:123], v86, s[34:35]
	global_load_dwordx4 v[124:127], v86, s[24:25]
	global_load_dwordx4 v[128:131], v86, s[22:23]
	global_load_dwordx4 v[132:135], v86, s[20:21]
	global_load_dwordx4 v[136:139], v86, s[18:19]
	global_load_dwordx4 v[140:143], v86, s[14:15]
	global_load_dwordx4 v[144:147], v86, s[12:13]
	global_load_dwordx4 v[148:151], v86, s[26:27] offset:1024
	global_load_dwordx4 v[152:155], v86, s[28:29] offset:1024
	global_load_dwordx4 v[156:159], v86, s[30:31] offset:1024
	global_load_dwordx4 v[160:163], v86, s[34:35] offset:1024
	global_load_dwordx4 v[164:167], v86, s[24:25] offset:1024
	global_load_dwordx4 v[168:171], v86, s[22:23] offset:1024
	global_load_dwordx4 v[172:175], v86, s[20:21] offset:1024
	global_load_dwordx4 v[178:181], v86, s[18:19] offset:1024
	global_load_dwordx4 v[182:185], v86, s[14:15] offset:1024
	global_load_dwordx4 v[186:189], v86, s[12:13] offset:1024
	s_waitcnt vmcnt(0)
	v_pk_add_f32 v[0:1], v[108:109], v[116:117]
	v_pk_add_f32 v[2:3], v[110:111], v[118:119]
	v_pk_add_f32 v[0:1], v[0:1], v[124:125]
	v_pk_add_f32 v[2:3], v[2:3], v[126:127]
	v_pk_add_f32 v[0:1], v[0:1], v[132:133]
	v_pk_add_f32 v[2:3], v[2:3], v[134:135]
	v_pk_add_f32 v[0:1], v[0:1], v[140:141]
	v_pk_add_f32 v[2:3], v[2:3], v[142:143]
	v_pk_add_f32 v[4:5], v[112:113], v[120:121]
	v_pk_add_f32 v[6:7], v[114:115], v[122:123]
	v_pk_add_f32 v[4:5], v[4:5], v[128:129]
	v_pk_add_f32 v[6:7], v[6:7], v[130:131]
	v_pk_add_f32 v[4:5], v[4:5], v[136:137]
	v_pk_add_f32 v[6:7], v[6:7], v[138:139]
	v_pk_add_f32 v[4:5], v[4:5], v[144:145]
	v_pk_add_f32 v[6:7], v[6:7], v[146:147]
	v_pk_add_f32 v[12:13], v[148:149], v[156:157]
	v_pk_add_f32 v[14:15], v[150:151], v[158:159]
	v_pk_add_f32 v[12:13], v[12:13], v[164:165]
	v_pk_add_f32 v[14:15], v[14:15], v[166:167]
	v_pk_add_f32 v[12:13], v[12:13], v[172:173]
	v_pk_add_f32 v[14:15], v[14:15], v[174:175]
	v_pk_add_f32 v[12:13], v[12:13], v[182:183]
	v_pk_add_f32 v[14:15], v[14:15], v[184:185]
	v_pk_add_f32 v[8:9], v[152:153], v[160:161]
	v_pk_add_f32 v[10:11], v[154:155], v[162:163]
	v_pk_add_f32 v[8:9], v[8:9], v[168:169]
	v_pk_add_f32 v[10:11], v[10:11], v[170:171]
	v_pk_add_f32 v[8:9], v[8:9], v[178:179]
	v_pk_add_f32 v[10:11], v[10:11], v[180:181]
	v_pk_add_f32 v[8:9], v[8:9], v[186:187]
	v_pk_add_f32 v[10:11], v[10:11], v[188:189]
	global_load_dwordx4 v[108:111], v86, s[26:27] offset:2048
	global_load_dwordx4 v[112:115], v86, s[28:29] offset:2048
	global_load_dwordx4 v[116:119], v86, s[30:31] offset:2048
	global_load_dwordx4 v[120:123], v86, s[34:35] offset:2048
	global_load_dwordx4 v[124:127], v86, s[24:25] offset:2048
	global_load_dwordx4 v[128:131], v86, s[22:23] offset:2048
	global_load_dwordx4 v[132:135], v86, s[20:21] offset:2048
	global_load_dwordx4 v[136:139], v86, s[18:19] offset:2048
	global_load_dwordx4 v[140:143], v86, s[14:15] offset:2048
	global_load_dwordx4 v[144:147], v86, s[12:13] offset:2048
	global_load_dwordx4 v[148:151], v86, s[26:27] offset:3072
	global_load_dwordx4 v[152:155], v86, s[28:29] offset:3072
	global_load_dwordx4 v[156:159], v86, s[30:31] offset:3072
	global_load_dwordx4 v[160:163], v86, s[34:35] offset:3072
	global_load_dwordx4 v[164:167], v86, s[24:25] offset:3072
	global_load_dwordx4 v[168:171], v86, s[22:23] offset:3072
	global_load_dwordx4 v[172:175], v86, s[20:21] offset:3072
	global_load_dwordx4 v[178:181], v86, s[18:19] offset:3072
	global_load_dwordx4 v[182:185], v86, s[14:15] offset:3072
	global_load_dwordx4 v[186:189], v86, s[12:13] offset:3072
	s_mov_b32 s18, s5
	s_waitcnt vmcnt(0)
	v_pk_add_f32 v[16:17], v[108:109], v[116:117]
	v_pk_add_f32 v[18:19], v[110:111], v[118:119]
	v_pk_add_f32 v[16:17], v[16:17], v[124:125]
	v_pk_add_f32 v[18:19], v[18:19], v[126:127]
	v_pk_add_f32 v[16:17], v[16:17], v[132:133]
	v_pk_add_f32 v[18:19], v[18:19], v[134:135]
	v_pk_add_f32 v[16:17], v[16:17], v[140:141]
	v_pk_add_f32 v[18:19], v[18:19], v[142:143]
	v_pk_add_f32 v[20:21], v[112:113], v[120:121]
	v_pk_add_f32 v[22:23], v[114:115], v[122:123]
	v_pk_add_f32 v[20:21], v[20:21], v[128:129]
	v_pk_add_f32 v[22:23], v[22:23], v[130:131]
	v_pk_add_f32 v[20:21], v[20:21], v[136:137]
	v_pk_add_f32 v[22:23], v[22:23], v[138:139]
	v_pk_add_f32 v[20:21], v[20:21], v[144:145]
	v_pk_add_f32 v[22:23], v[22:23], v[146:147]
	v_pk_add_f32 v[24:25], v[148:149], v[156:157]
	v_pk_add_f32 v[26:27], v[150:151], v[158:159]
	v_pk_add_f32 v[24:25], v[24:25], v[164:165]
	v_pk_add_f32 v[26:27], v[26:27], v[166:167]
	v_pk_add_f32 v[24:25], v[24:25], v[172:173]
	v_pk_add_f32 v[26:27], v[26:27], v[174:175]
	v_pk_add_f32 v[24:25], v[24:25], v[182:183]
	v_pk_add_f32 v[26:27], v[26:27], v[184:185]
	v_pk_add_f32 v[28:29], v[152:153], v[160:161]
	v_pk_add_f32 v[30:31], v[154:155], v[162:163]
	v_pk_add_f32 v[28:29], v[28:29], v[168:169]
	v_pk_add_f32 v[30:31], v[30:31], v[170:171]
	v_pk_add_f32 v[28:29], v[28:29], v[178:179]
	v_pk_add_f32 v[30:31], v[30:31], v[180:181]
	v_pk_add_f32 v[28:29], v[28:29], v[186:187]
	v_pk_add_f32 v[30:31], v[30:31], v[188:189]
	s_nop 0
	s_nop 0
	s_nop 0
	s_nop 0
	s_nop 0
	s_nop 0
	s_nop 0
	s_nop 0
	s_nop 0
	s_nop 0
	s_nop 0
	s_nop 0
	s_nop 0
	s_nop 0
